# streaming hint: the layer-0 rmsnorm reads the input activations with non-temporal loads so they do not displace the bf16 activations and weights the next GEMM phase reuses
# speedup vs baseline: 1.0127x; 1.0065x over previous
; DI void rmsnorm_phase(const float* __restrict__ X, const float* __restrict__ g, bf16_t* __restrict__ H, float* __restrict__ OF) {
;     ...
;   for (int row = gw; row < T; row += nw) {
;     const float* xr = X + (size_t)row * D;
;     f32x4 v[8];
;     float ss = 0.f;
; #pragma unroll
;     for (int i = 0; i < 8; ++i) { v[i] = *(const f32x4*)(xr + lane * 4 + 256 * i); ss += v[i][0] * v[i][0] + v[i][1] * v[i][1] + v[i][2] * v[i][2] + v[i][3] * v[i][3]; }
;     ss = wave_sum(ss);
;     const float rstd = rsqrtf(ss * (1.f / D) + EPS);
; #pragma unroll
;     for (int i = 0; i < 8; ++i) {
;       const f32x4 gg = *(const f32x4*)(g + lane * 4 + 256 * i);
;       f32x4 o = v[i] * rstd * gg;
;       if (H) { u32x2 w; w.x = pk_bf16(o[0], o[1]); w.y = pk_bf16(o[2], o[3]); *(u32x2*)(H + (size_t)row * D + lane * 4 + 256 * i) = w; }
;       else *(f32x4*)(OF + (size_t)row * D + lane * 4 + 256 * i) = o;
;     }
;   }
.LBB0_83:
	global_load_dwordx4 v[38:41], v[52:53], off nt
	global_load_dwordx4 v[34:37], v[52:53], off offset:1024 nt
	global_load_dwordx4 v[46:49], v[52:53], off offset:2048 nt
	global_load_dwordx4 v[42:45], v[52:53], off offset:3072 nt
	global_load_dwordx4 v[62:65], v[52:53], off offset:-4096 nt
	global_load_dwordx4 v[66:69], v[52:53], off offset:-3072 nt
	global_load_dwordx4 v[70:73], v[52:53], off offset:-2048 nt
	global_load_dwordx4 v[74:77], v[52:53], off offset:-1024 nt
	v_add_u32_e32 v50, s4, v50
	v_cmp_lt_i32_e32 vcc, s12, v50
	s_or_b64 s[10:11], vcc, s[10:11]
	v_lshl_add_u64 v[52:53], v[52:53], 0, s[6:7]
	s_waitcnt vmcnt(7)
	v_mov_b32_e32 v80, v39
	s_waitcnt vmcnt(6)
	v_mov_b32_e32 v81, v35
	v_mov_b32_e32 v78, v38
	v_mov_b32_e32 v79, v34
	s_waitcnt vmcnt(3)
	v_mul_f32_e32 v61, v63, v63
	s_waitcnt vmcnt(2)
	v_mul_f32_e32 v94, v67, v67
	s_waitcnt vmcnt(1)
	v_mul_f32_e32 v95, v71, v71
	v_fmac_f32_e32 v61, v62, v62
	v_fmac_f32_e32 v94, v66, v66
	s_waitcnt vmcnt(0)
	v_mul_f32_e32 v96, v75, v75
	v_fmac_f32_e32 v95, v70, v70
	v_fmac_f32_e32 v61, v64, v64
	v_fmac_f32_e32 v94, v68, v68
	v_pk_mul_f32 v[80:81], v[80:81], v[80:81]
	v_fmac_f32_e32 v96, v74, v74
	v_fmac_f32_e32 v95, v72, v72
	v_fmac_f32_e32 v61, v65, v65
	v_fmac_f32_e32 v94, v69, v69
	v_mov_b32_e32 v84, v47
	v_mov_b32_e32 v85, v43
	v_mov_b32_e32 v86, v40
	v_mov_b32_e32 v87, v36
	v_pk_fma_f32 v[78:79], v[78:79], v[78:79], v[80:81]
	v_fmac_f32_e32 v96, v76, v76
	v_fmac_f32_e32 v95, v73, v73
	v_add_f32_e32 v61, v61, v94
	v_mov_b32_e32 v82, v46
	v_mov_b32_e32 v83, v42
	v_mov_b32_e32 v90, v41
	v_mov_b32_e32 v91, v37
	v_pk_mul_f32 v[84:85], v[84:85], v[84:85]
	v_pk_fma_f32 v[78:79], v[86:87], v[86:87], v[78:79]
	v_fmac_f32_e32 v96, v77, v77
	v_add_f32_e32 v61, v61, v95
	v_mov_b32_e32 v88, v48
	v_mov_b32_e32 v89, v44
	v_pk_fma_f32 v[80:81], v[82:83], v[82:83], v[84:85]
	v_pk_fma_f32 v[78:79], v[90:91], v[90:91], v[78:79]
	v_add_f32_e32 v61, v61, v96
	v_mov_b32_e32 v92, v49
	v_mov_b32_e32 v93, v45
	v_pk_fma_f32 v[80:81], v[88:89], v[88:89], v[80:81]
	v_add_f32_e32 v61, v61, v78
	v_pk_fma_f32 v[80:81], v[92:93], v[92:93], v[80:81]
	v_add_f32_e32 v61, v61, v79
	v_add_f32_e32 v61, v61, v80
	v_add_f32_e32 v61, v61, v81
	ds_bpermute_b32 v78, v1, v61
	s_waitcnt lgkmcnt(0)
	v_add_f32_e32 v61, v61, v78
	ds_bpermute_b32 v78, v56, v61
	s_waitcnt lgkmcnt(0)
	v_add_f32_e32 v61, v61, v78
	ds_bpermute_b32 v78, v57, v61
	s_waitcnt lgkmcnt(0)
	v_add_f32_e32 v61, v61, v78
	ds_bpermute_b32 v78, v58, v61
	s_waitcnt lgkmcnt(0)
	v_add_f32_e32 v61, v61, v78
	ds_bpermute_b32 v78, v59, v61
	s_waitcnt lgkmcnt(0)
	v_add_f32_e32 v61, v61, v78
	ds_bpermute_b32 v78, v60, v61
	s_waitcnt lgkmcnt(0)
	v_add_f32_e32 v61, v61, v78
	v_fmamk_f32 v61, v61, 0x3a000000, v51
	v_mul_f32_e32 v78, 0x4b800000, v61
	v_cmp_gt_f32_e32 vcc, s5, v61
	s_nop 1
	v_cndmask_b32_e32 v61, v61, v78, vcc
	v_rsq_f32_e32 v61, v61
	s_nop 0
	v_mul_f32_e32 v78, 0x45800000, v61
	v_cndmask_b32_e32 v78, v61, v78, vcc
	v_pk_mul_f32 v[62:63], v[62:63], v[78:79] op_sel_hi:[1,0]
	v_pk_mul_f32 v[64:65], v[64:65], v[78:79] op_sel_hi:[1,0]
	v_pk_mul_f32 v[66:67], v[66:67], v[78:79] op_sel_hi:[1,0]
	v_pk_mul_f32 v[68:69], v[68:69], v[78:79] op_sel_hi:[1,0]
	v_pk_mul_f32 v[70:71], v[70:71], v[78:79] op_sel_hi:[1,0]
	v_pk_mul_f32 v[72:73], v[72:73], v[78:79] op_sel_hi:[1,0]
	v_pk_mul_f32 v[74:75], v[74:75], v[78:79] op_sel_hi:[1,0]
	v_pk_mul_f32 v[76:77], v[76:77], v[78:79] op_sel_hi:[1,0]
	v_pk_mul_f32 v[38:39], v[38:39], v[78:79] op_sel_hi:[1,0]
	v_pk_mul_f32 v[40:41], v[40:41], v[78:79] op_sel_hi:[1,0]
	v_pk_mul_f32 v[34:35], v[34:35], v[78:79] op_sel_hi:[1,0]
	v_pk_mul_f32 v[36:37], v[36:37], v[78:79] op_sel_hi:[1,0]
	v_pk_mul_f32 v[46:47], v[46:47], v[78:79] op_sel_hi:[1,0]
	v_pk_mul_f32 v[48:49], v[48:49], v[78:79] op_sel_hi:[1,0]
	v_pk_mul_f32 v[42:43], v[42:43], v[78:79] op_sel_hi:[1,0]
	v_pk_mul_f32 v[44:45], v[44:45], v[78:79] op_sel_hi:[1,0]
	v_pk_mul_f32 v[64:65], v[4:5], v[64:65]
	v_pk_mul_f32 v[62:63], v[2:3], v[62:63]
	v_pk_mul_f32 v[68:69], v[8:9], v[68:69]
	v_pk_mul_f32 v[66:67], v[6:7], v[66:67]
	v_pk_mul_f32 v[72:73], v[12:13], v[72:73]
	v_pk_mul_f32 v[70:71], v[10:11], v[70:71]
	v_pk_mul_f32 v[76:77], v[16:17], v[76:77]
	v_pk_mul_f32 v[74:75], v[14:15], v[74:75]
	v_pk_mul_f32 v[40:41], v[20:21], v[40:41]
	v_pk_mul_f32 v[38:39], v[18:19], v[38:39]
	v_pk_mul_f32 v[36:37], v[24:25], v[36:37]
	v_pk_mul_f32 v[34:35], v[22:23], v[34:35]
	v_pk_mul_f32 v[48:49], v[28:29], v[48:49]
	v_pk_mul_f32 v[46:47], v[26:27], v[46:47]
	v_pk_mul_f32 v[44:45], v[32:33], v[44:45]
	v_pk_mul_f32 v[42:43], v[30:31], v[42:43]
	v_cvt_pk_bf16_f32 v62, v62, v63
	v_cvt_pk_bf16_f32 v63, v64, v65
	v_cvt_pk_bf16_f32 v64, v66, v67
	v_cvt_pk_bf16_f32 v65, v68, v69
	v_cvt_pk_bf16_f32 v66, v70, v71
	v_cvt_pk_bf16_f32 v67, v72, v73
	v_cvt_pk_bf16_f32 v68, v74, v75
	v_cvt_pk_bf16_f32 v69, v76, v77
	v_cvt_pk_bf16_f32 v38, v38, v39
	v_cvt_pk_bf16_f32 v39, v40, v41
	v_cvt_pk_bf16_f32 v34, v34, v35
	v_cvt_pk_bf16_f32 v35, v36, v37
	v_cvt_pk_bf16_f32 v36, v46, v47
	v_cvt_pk_bf16_f32 v37, v48, v49
	v_cvt_pk_bf16_f32 v40, v42, v43
	v_cvt_pk_bf16_f32 v41, v44, v45
	global_store_dwordx2 v[54:55], v[62:63], off
	global_store_dwordx2 v[54:55], v[64:65], off offset:512
	global_store_dwordx2 v[54:55], v[66:67], off offset:1024
	global_store_dwordx2 v[54:55], v[68:69], off offset:1536
	global_store_dwordx2 v[54:55], v[38:39], off offset:2048
	global_store_dwordx2 v[54:55], v[34:35], off offset:2560
	global_store_dwordx2 v[54:55], v[36:37], off offset:3072
	global_store_dwordx2 v[54:55], v[40:41], off offset:3584
	v_lshl_add_u64 v[54:55], v[54:55], 0, s[8:9]
	s_andn2_b64 exec, exec, s[10:11]
	s_cbranch_execnz .LBB0_83
